# removed the redundant end-of-GEMM-phase barrier where the seam entry barrier follows immediately (8 sites)
# speedup vs baseline: 1.0054x; 1.0015x over previous
.LBB0_353:
	s_waitcnt vmcnt(0)
.LBB0_354:
	s_waitcnt vmcnt(0)
	s_and_b64 vcc, exec, s[2:3]
	s_waitcnt lgkmcnt(0)
	s_barrier
	s_cbranch_vccnz .LBB0_408
	v_mbcnt_lo_u32_b32 v0, -1, 0
	v_mbcnt_hi_u32_b32 v0, -1, v0
	s_nop 0
	v_cmp_eq_u32_e32 vcc, 0, v0
	s_and_saveexec_b64 s[6:7], vcc
	s_cbranch_execz .LBB0_407
	s_cmp_eq_u32 s101, 1
	s_cbranch_scc0 .Lglob_S3
	s_and_b32 s98, s33, 7
	s_lshl_b32 s99, s98, 2
	s_addk_i32 s99, 0x4800
	v_mov_b32_e32 v3, s99
	s_lshl_b32 s98, s98, 8
	s_addk_i32 s98, 0x4000
	v_mov_b32_e32 v0, s98
	v_mov_b32_e32 v1, 1
	global_atomic_add v2, v0, v1, s[44:45] sc0
	buffer_inv sc1
	s_waitcnt vmcnt(1)
	v_readfirstlane_b32 s98, v2
	s_nop 3
	s_add_u32 s99, s98, 1
	s_and_b32 s99, s99, 31
	s_lshr_b32 s98, s98, 5
	s_cmp_eq_u32 s99, 0
	s_cbranch_scc0 .Llw_S3
	global_atomic_add v3, v1, s[44:45]
	s_branch .Lla_S3

.LBB0_681:
	s_waitcnt vmcnt(0)
.LBB0_682:
	s_waitcnt vmcnt(0)
	s_and_b64 vcc, exec, s[2:3]
	s_waitcnt vmcnt(0)
	s_barrier
	s_cbranch_vccnz .LBB0_736
	v_mbcnt_lo_u32_b32 v0, -1, 0
	v_mbcnt_hi_u32_b32 v0, -1, v0
	s_nop 0
	v_cmp_eq_u32_e32 vcc, 0, v0
	s_and_saveexec_b64 s[6:7], vcc
	s_cbranch_execz .LBB0_735
	s_cmp_eq_u32 s101, 1
	s_cbranch_scc0 .Lglob_S4
	s_and_b32 s98, s33, 7
	s_lshl_b32 s99, s98, 2
	s_addk_i32 s99, 0x4800
	v_mov_b32_e32 v3, s99
	s_lshl_b32 s98, s98, 8
	s_addk_i32 s98, 0x4000
	v_mov_b32_e32 v0, s98
	v_mov_b32_e32 v1, 1
	global_atomic_add v2, v0, v1, s[44:45] sc0
	buffer_inv sc1
	s_waitcnt vmcnt(1)
	v_readfirstlane_b32 s98, v2
	s_nop 3
	s_add_u32 s99, s98, 1
	s_and_b32 s99, s99, 31
	s_lshr_b32 s98, s98, 5
	s_cmp_eq_u32 s99, 0
	s_cbranch_scc0 .Llw_S4
	global_atomic_add v3, v1, s[44:45]
	s_branch .Lla_S4

.LBB0_846:
	s_waitcnt vmcnt(0)
.LBB0_847:
	s_waitcnt vmcnt(0)
	s_and_b64 vcc, exec, s[2:3]
	s_waitcnt lgkmcnt(0)
	s_barrier
	s_cbranch_vccnz .LBB0_901
	v_mbcnt_lo_u32_b32 v0, -1, 0
	v_mbcnt_hi_u32_b32 v0, -1, v0
	s_nop 0
	v_cmp_eq_u32_e32 vcc, 0, v0
	s_and_saveexec_b64 s[6:7], vcc
	s_cbranch_execz .LBB0_900
	s_cmp_eq_u32 s101, 1
	s_cbranch_scc0 .Lglob_S6
	s_and_b32 s98, s33, 7
	s_lshl_b32 s99, s98, 2
	s_addk_i32 s99, 0x4800
	v_mov_b32_e32 v3, s99
	s_lshl_b32 s98, s98, 8
	s_addk_i32 s98, 0x4000
	v_mov_b32_e32 v0, s98
	v_mov_b32_e32 v1, 1
	global_atomic_add v2, v0, v1, s[44:45] sc0
	buffer_inv sc1
	s_waitcnt vmcnt(1)
	v_readfirstlane_b32 s98, v2
	s_nop 3
	s_add_u32 s99, s98, 1
	s_and_b32 s99, s99, 31
	s_lshr_b32 s98, s98, 5
	s_cmp_eq_u32 s99, 0
	s_cbranch_scc0 .Llw_S6
	global_atomic_add v3, v1, s[44:45]
	s_branch .Lla_S6

.LBB0_1212:
	s_waitcnt vmcnt(0)
.LBB0_1213:
	s_waitcnt vmcnt(0)
	s_and_b64 vcc, exec, s[2:3]
	s_waitcnt lgkmcnt(0)
	s_barrier
	s_cbranch_vccnz .LBB0_1267
	v_mbcnt_lo_u32_b32 v0, -1, 0
	v_mbcnt_hi_u32_b32 v0, -1, v0
	s_nop 0
	v_cmp_eq_u32_e32 vcc, 0, v0
	s_and_saveexec_b64 s[8:9], vcc
	s_cbranch_execz .LBB0_1266
	s_cmp_eq_u32 s101, 1
	s_cbranch_scc0 .Lglob_S8
	s_and_b32 s98, s33, 7
	s_lshl_b32 s99, s98, 2
	s_addk_i32 s99, 0x4800
	v_mov_b32_e32 v3, s99
	s_lshl_b32 s98, s98, 8
	s_addk_i32 s98, 0x4000
	v_mov_b32_e32 v0, s98
	v_mov_b32_e32 v1, 1
	global_atomic_add v2, v0, v1, s[44:45] sc0
	buffer_inv sc1
	s_waitcnt vmcnt(1)
	v_readfirstlane_b32 s98, v2
	s_nop 3
	s_add_u32 s99, s98, 1
	s_and_b32 s99, s99, 31
	s_lshr_b32 s98, s98, 5
	s_cmp_eq_u32 s99, 0
	s_cbranch_scc0 .Llw_S8
	global_atomic_add v3, v1, s[44:45]
	s_branch .Lla_S8

.LBB0_1690:
	s_waitcnt vmcnt(0)
.LBB0_1691:
	s_waitcnt vmcnt(0)
	s_and_b64 vcc, exec, s[2:3]
	s_waitcnt lgkmcnt(0)
	s_barrier
	s_cbranch_vccnz .LBB0_1745
	v_mbcnt_lo_u32_b32 v0, -1, 0
	v_mbcnt_hi_u32_b32 v0, -1, v0
	s_nop 0
	v_cmp_eq_u32_e32 vcc, 0, v0
	s_and_saveexec_b64 s[8:9], vcc
	s_cbranch_execz .LBB0_1744
	s_cmp_eq_u32 s101, 1
	s_cbranch_scc0 .Lglob_S10
	s_and_b32 s98, s33, 7
	s_lshl_b32 s99, s98, 2
	s_addk_i32 s99, 0x4800
	v_mov_b32_e32 v3, s99
	s_lshl_b32 s98, s98, 8
	s_addk_i32 s98, 0x4000
	v_mov_b32_e32 v0, s98
	v_mov_b32_e32 v1, 1
	global_atomic_add v2, v0, v1, s[44:45] sc0
	v_mov_b32_e32 v5, 0x5108
	global_load_dword v5, v5, s[44:45] sc1
	buffer_inv sc1
	s_waitcnt vmcnt(2)
	v_readfirstlane_b32 s98, v2
	s_nop 3
	s_add_u32 s99, s98, 1
	s_and_b32 s99, s99, 31
	s_lshr_b32 s98, s98, 5
	s_cmp_eq_u32 s99, 0
	s_cbranch_scc0 .Llw_S10
	global_atomic_add v3, v1, s[44:45]
	s_branch .Lla_S10

.LBB0_2026:
	s_waitcnt vmcnt(0)
.LBB0_2027:
	s_waitcnt vmcnt(0)
	s_and_b64 vcc, exec, s[2:3]
	s_waitcnt vmcnt(0)
	s_barrier
	s_cbranch_vccnz .LBB0_2081
	v_mbcnt_lo_u32_b32 v0, -1, 0
	v_mbcnt_hi_u32_b32 v0, -1, v0
	s_nop 0
	v_cmp_eq_u32_e32 vcc, 0, v0
	s_and_saveexec_b64 s[8:9], vcc
	s_cbranch_execz .LBB0_2080
	s_cmp_eq_u32 s101, 1
	s_cbranch_scc0 .Lglob_S11
	s_and_b32 s98, s33, 7
	s_lshl_b32 s99, s98, 2
	s_addk_i32 s99, 0x4800
	v_mov_b32_e32 v3, s99
	s_lshl_b32 s98, s98, 8
	s_addk_i32 s98, 0x4000
	v_mov_b32_e32 v0, s98
	v_mov_b32_e32 v1, 1
	global_atomic_add v2, v0, v1, s[44:45] sc0
	buffer_inv sc1
	s_waitcnt vmcnt(1)
	v_readfirstlane_b32 s98, v2
	s_nop 3
	s_add_u32 s99, s98, 1
	s_and_b32 s99, s99, 31
	s_lshr_b32 s98, s98, 5
	s_cmp_eq_u32 s99, 0
	s_cbranch_scc0 .Llw_S11
	global_atomic_add v3, v1, s[44:45]
	s_branch .Lla_S11

.LBB0_2326:
	s_waitcnt vmcnt(0)
.LBB0_2327:
	s_waitcnt vmcnt(0)
	s_and_b64 vcc, exec, s[2:3]
	s_waitcnt lgkmcnt(0)
	s_barrier
	s_cbranch_vccnz .LBB0_2381
	v_mbcnt_lo_u32_b32 v0, -1, 0
	v_mbcnt_hi_u32_b32 v0, -1, v0
	s_nop 0
	v_cmp_eq_u32_e32 vcc, 0, v0
	s_and_saveexec_b64 s[8:9], vcc
	s_cbranch_execz .LBB0_2380
	s_cmp_eq_u32 s101, 1
	s_cbranch_scc0 .Lglob_S13
	s_and_b32 s98, s33, 7
	s_lshl_b32 s99, s98, 2
	s_addk_i32 s99, 0x4800
	v_mov_b32_e32 v3, s99
	s_lshl_b32 s98, s98, 8
	s_addk_i32 s98, 0x4000
	v_mov_b32_e32 v0, s98
	v_mov_b32_e32 v1, 1
	global_atomic_add v2, v0, v1, s[44:45] sc0
	buffer_inv sc1
	s_waitcnt vmcnt(1)
	v_readfirstlane_b32 s98, v2
	s_nop 3
	s_add_u32 s99, s98, 1
	s_and_b32 s99, s99, 31
	s_lshr_b32 s98, s98, 5
	s_cmp_eq_u32 s99, 0
	s_cbranch_scc0 .Llw_S13
	global_atomic_add v3, v1, s[44:45]
	s_branch .Lla_S13

.LBB0_2396:
	s_waitcnt vmcnt(0)
.LBB0_2397:
	s_waitcnt vmcnt(0)
	s_and_b64 vcc, exec, s[2:3]
	s_waitcnt vmcnt(0)
	s_barrier
	s_cbranch_vccnz .LBB0_2451
	v_mbcnt_lo_u32_b32 v0, -1, 0
	v_mbcnt_hi_u32_b32 v0, -1, v0
	s_nop 0
	v_cmp_eq_u32_e32 vcc, 0, v0
	s_and_saveexec_b64 s[2:3], vcc
	s_cbranch_execz .LBB0_2450
	s_cmp_eq_u32 s101, 1
	s_cbranch_scc0 .Lglob_S14
	s_and_b32 s98, s33, 7
	s_lshl_b32 s99, s98, 2
	s_addk_i32 s99, 0x4800
	v_mov_b32_e32 v3, s99
	s_lshl_b32 s98, s98, 8
	s_addk_i32 s98, 0x4000
	v_mov_b32_e32 v0, s98
	v_mov_b32_e32 v1, 1
	global_atomic_add v2, v0, v1, s[44:45] sc0
	buffer_inv sc1
	s_waitcnt vmcnt(1)
	v_readfirstlane_b32 s98, v2
	s_nop 3
	s_add_u32 s99, s98, 1
	s_and_b32 s99, s99, 31
	s_lshr_b32 s98, s98, 5
	s_cmp_eq_u32 s99, 0
	s_cbranch_scc0 .Llw_S14
	global_atomic_add v3, v1, s[44:45]
	s_branch .Lla_S14
